# sample attention loop first half hand-rewritten: tile stores and next-tile prefetch woven between QK MFMAs, incremental prefetch addresses, q switch as branch
# baseline (speedup 1.0000x reference)
.LBB0_374:
	s_andn2_saveexec_b64 s[0:1], s[0:1]
	v_lshlrev_b64 v[0:1], 10, v[2:3]
	v_lshl_add_u64 v[0:1], s[2:3], 0, v[0:1]
	v_mov_b32_e32 v13, v137
	v_lshl_add_u64 v[0:1], v[0:1], 0, v[12:13]
	s_or_b64 exec, exec, s[0:1]
	s_ashr_i32 s71, s70, 31
	s_lshl_b64 s[0:1], s[70:71], 1
	v_readlane_b32 s4, v252, 63
	v_readlane_b32 s5, v253, 0
	s_add_u32 s0, s4, s0
	s_addc_u32 s1, s5, s1
	v_mov_b32_e32 v15, v137
	global_load_dwordx4 v[104:107], v[0:1], off
	v_lshl_add_u64 v[0:1], s[0:1], 0, v[14:15]
	v_lshl_add_u64 v[2:3], v[0:1], 0, v[136:137]
	v_mov_b32_e32 v121, v137
	v_lshl_add_u64 v[0:1], v[0:1], 0, v[120:121]
	global_load_dwordx4 v[108:111], v[2:3], off
	global_load_dwordx4 v[112:115], v[0:1], off
	v_lshl_add_u64 v[122:123], s[4:5], 0, v[14:15]
	v_readlane_b32 s4, v253, 3
	s_add_i32 s0, s22, 0x2080
	v_mov_b32_e32 v9, v137
	v_readlane_b32 s5, v253, 4
	v_mov_b32_e32 v11, v137
	v_mov_b32_e32 v13, v137
	v_mov_b32_e32 v14, v137
	v_lshlrev_b32_e32 v118, 3, v19
	v_mul_u32_u24_e32 v152, 0x90, v16
	v_mul_u32_u24_e32 v153, 0x90, v17
	v_lshl_add_u32 v154, v19, 4, s24
	v_lshl_add_u64 v[124:125], s[4:5], 0, v[8:9]
	v_lshl_add_u64 v[126:127], s[2:3], 0, v[8:9]
	v_lshl_add_u64 v[128:129], s[4:5], 0, v[10:11]
	v_lshl_add_u64 v[130:131], s[2:3], 0, v[10:11]
	v_lshl_add_u64 v[132:133], s[4:5], 0, v[12:13]
	v_lshl_add_u64 v[134:135], s[2:3], 0, v[12:13]
	v_mul_u32_u24_e32 v155, 0xd0, v18
	v_mul_u32_u24_e32 v142, 0x90, v18
	v_add_u32_sdwa v156, s0, v22 dst_sel:DWORD dst_unused:UNUSED_PAD src0_sel:DWORD src1_sel:WORD_1
	v_add_u32_sdwa v157, s0, v21 dst_sel:DWORD dst_unused:UNUSED_PAD src0_sel:DWORD src1_sel:WORD_1
	v_add_u32_e32 v158, s0, v20
	v_mov_b32_e32 v0, v137
	v_mov_b32_e32 v1, v137
	v_mov_b32_e32 v2, v137
	v_mov_b32_e32 v3, v137
	v_mov_b32_e32 v4, v137
	v_mov_b32_e32 v5, v137
	v_mov_b32_e32 v6, v137
	v_mov_b32_e32 v7, v137
	v_mov_b32_e32 v8, v137
	v_mov_b32_e32 v10, v137
	v_mov_b32_e32 v12, v137
	v_mov_b64_e32 v[30:31], v[14:15]
	v_add_u32_e32 v143, s24, v118
	s_mov_b32 s1, 0
	v_mov_b32_e32 v151, 0xf149f2ca
	v_mov_b32_e32 v119, 0
	v_mov_b64_e32 v[28:29], v[12:13]
	v_mov_b64_e32 v[26:27], v[10:11]
	v_mov_b64_e32 v[24:25], v[8:9]
	v_mov_b64_e32 v[22:23], v[6:7]
	v_mov_b64_e32 v[20:21], v[4:5]
	v_mov_b64_e32 v[18:19], v[2:3]
	v_mov_b64_e32 v[16:17], v[0:1]
	s_mov_b32 s3, 0
	s_movk_i32 s4, 0xff80
	s_mov_b32 s5, -1
	v_mov_b32_e32 v238, 0x1000
	v_mov_b32_e32 v239, 0x10000
	v_add_u32_e32 v32, s1, v158
	v_ashrrev_i32_e32 v33, 31, v32
	v_lshlrev_b64 v[34:35], 10, v[32:33]
	v_lshlrev_b64 v[32:33], 6, v[32:33]
	v_lshl_add_u64 v[32:33], v[124:125], 0, v[32:33]
	v_lshl_add_u64 v[34:35], v[126:127], 0, v[34:35]
	v_lshl_add_u64 v[32:33], v[32:33], 0, s[4:5]
	v_cndmask_b32_e64 v241, v33, v35, s[40:41]
	v_cndmask_b32_e64 v240, v32, v34, s[40:41]
	v_add_u32_e32 v32, s1, v157
	v_ashrrev_i32_e32 v33, 31, v32
	v_lshlrev_b64 v[34:35], 10, v[32:33]
	v_lshlrev_b64 v[32:33], 6, v[32:33]
	v_lshl_add_u64 v[32:33], v[128:129], 0, v[32:33]
	v_lshl_add_u64 v[34:35], v[130:131], 0, v[34:35]
	v_lshl_add_u64 v[32:33], v[32:33], 0, s[4:5]
	v_cndmask_b32_e64 v243, v33, v35, s[42:43]
	v_cndmask_b32_e64 v242, v32, v34, s[42:43]
	v_add_u32_e32 v32, s1, v156
	v_ashrrev_i32_e32 v33, 31, v32
	v_lshlrev_b64 v[34:35], 10, v[32:33]
	v_lshlrev_b64 v[32:33], 6, v[32:33]
	v_lshl_add_u64 v[32:33], v[132:133], 0, v[32:33]
	v_lshl_add_u64 v[34:35], v[134:135], 0, v[34:35]
	v_lshl_add_u64 v[32:33], v[32:33], 0, s[4:5]
	v_cndmask_b32_e64 v245, v33, v35, s[44:45]
	v_cndmask_b32_e64 v244, v32, v34, s[44:45]
	s_add_i32 s22, s0, s1
	s_ashr_i32 s23, s22, 31
	v_lshl_add_u64 v[32:33], s[22:23], 1, v[122:123]
	v_lshl_add_u64 v[246:247], v[32:33], 0, v[136:137]
	v_mov_b32_e32 v121, v137
	v_lshl_add_u64 v[248:249], v[32:33], 0, v[120:121]
	s_waitcnt lgkmcnt(0)
	s_barrier
	v_readfirstlane_b32 s22, v139
	s_bitcmp1_b32 s22, 8
	s_cbranch_scc0 .Lsa_no_e1
	s_barrier
.Lsa_no_e1:
.LBB0_377:
	s_and_b32 s22, s3, 1
	s_mul_i32 s22, s22, 0x3400
	v_add3_u32 v160, v154, s22, v155
	ds_read_b128 v[190:193], v160
	ds_read_b128 v[194:197], v160 offset:32
	ds_read_b128 v[198:201], v160 offset:64
	ds_read_b128 v[202:205], v160 offset:96
	ds_read_b128 v[206:209], v160 offset:128
	ds_read_b128 v[210:213], v160 offset:160
	ds_read_b128 v[214:217], v160 offset:6656
	ds_read_b128 v[218:221], v160 offset:6688
	ds_read_b128 v[222:225], v160 offset:6720
	ds_read_b128 v[226:229], v160 offset:6752
	ds_read_b128 v[230:233], v160 offset:6784
	ds_read_b128 v[234:237], v160 offset:6816
	s_add_i32 s2, s3, 1
	s_bitcmp1_b32 s2, 0
	s_cselect_b32 s22, 0x3400, 0
	s_cselect_b32 s23, 0x2400, 0
	s_add_i32 s22, s24, s22
	s_and_b32 s3, s3, 1
	s_cmpk_lg_i32 s1, 0x200
	s_cbranch_scc1 .Lsa_noq
	v_mov_b32_e32 v67, v95
	v_mov_b32_e32 v66, v94
	v_mov_b32_e32 v65, v93
	v_mov_b32_e32 v64, v92
	v_mov_b32_e32 v71, v91
	v_mov_b32_e32 v70, v90
	v_mov_b32_e32 v69, v89
	v_mov_b32_e32 v68, v88
.Lsa_noq:
	v_add3_u32 v160, s22, v144, v145
	v_add3_u32 v161, s22, v146, v147
	s_setprio 1
	s_waitcnt lgkmcnt(0)
	v_mfma_f32_32x32x16_bf16 v[32:47], v[190:193], v[84:87], 0
	v_mfma_f32_32x32x16_bf16 v[48:63], v[214:217], v[84:87], 0
	s_waitcnt vmcnt(4)
	ds_write_b128 v160, v[96:99]
	v_add3_u32 v160, s22, v148, v149
	v_mfma_f32_32x32x16_bf16 v[32:47], v[194:197], v[80:83], v[32:47]
	v_mfma_f32_32x32x16_bf16 v[48:63], v[218:221], v[80:83], v[48:63]
	s_waitcnt vmcnt(3)
	ds_write_b128 v161, v[100:103]
	v_add_u32_e32 v161, s23, v150
	v_mfma_f32_32x32x16_bf16 v[32:47], v[198:201], v[76:79], v[32:47]
	v_mfma_f32_32x32x16_bf16 v[48:63], v[222:225], v[76:79], v[48:63]
	s_waitcnt vmcnt(2)
	ds_write_b128 v160, v[104:107]
	v_add_u32_e32 v160, v161, v152
	v_add_u32_e32 v161, v161, v153
	v_mfma_f32_32x32x16_bf16 v[32:47], v[202:205], v[72:75], v[32:47]
	v_mfma_f32_32x32x16_bf16 v[48:63], v[226:229], v[72:75], v[48:63]
	s_waitcnt vmcnt(1)
	ds_write_b128 v160, v[108:111] offset:26624
	s_waitcnt vmcnt(0)
	ds_write_b128 v161, v[112:115] offset:26624
	v_cndmask_b32_e64 v160, v238, v239, s[40:41]
	v_cndmask_b32_e64 v161, v238, v239, s[42:43]
	v_mfma_f32_32x32x16_bf16 v[32:47], v[206:209], v[68:71], v[32:47]
	v_mfma_f32_32x32x16_bf16 v[48:63], v[230:233], v[68:71], v[48:63]
	s_cmpk_gt_u32 s2, 0x46
	s_cbranch_scc1 .Lsa_nold
	global_load_dwordx4 v[96:99], v[240:241], off
	global_load_dwordx4 v[100:103], v[242:243], off
	global_load_dwordx4 v[104:107], v[244:245], off
	global_load_dwordx4 v[108:111], v[246:247], off
	global_load_dwordx4 v[112:115], v[248:249], off
.Lsa_nold:
	v_add_co_u32_e32 v240, vcc, v240, v160
	v_addc_co_u32_e32 v241, vcc, 0, v241, vcc
	v_add_co_u32_e32 v242, vcc, v242, v161
	v_addc_co_u32_e32 v243, vcc, 0, v243, vcc
	v_cndmask_b32_e64 v160, v238, v239, s[44:45]
	v_mfma_f32_32x32x16_bf16 v[32:47], v[210:213], v[64:67], v[32:47]
	v_mfma_f32_32x32x16_bf16 v[48:63], v[234:237], v[64:67], v[48:63]
	v_add_co_u32_e32 v244, vcc, v244, v160
	v_addc_co_u32_e32 v245, vcc, 0, v245, vcc
	v_add_co_u32_e32 v246, vcc, 0x80, v246
	v_addc_co_u32_e32 v247, vcc, 0, v247, vcc
	v_add_co_u32_e32 v248, vcc, 0x80, v248
	v_addc_co_u32_e32 v249, vcc, 0, v249, vcc
	s_setprio 0
	s_nop 10
	v_max_f32_e32 v121, v48, v48
	v_max_f32_e32 v159, v32, v32
	v_max_f32_e32 v121, v159, v121
	v_max3_f32 v121, v121, v33, v49
	v_max3_f32 v121, v121, v34, v50
	v_max3_f32 v121, v121, v35, v51
	v_max3_f32 v121, v121, v36, v52
	v_max3_f32 v121, v121, v37, v53
	v_max3_f32 v121, v121, v38, v54
	v_max3_f32 v121, v121, v39, v55
	v_max3_f32 v121, v121, v40, v56
	v_max3_f32 v121, v121, v41, v57
	v_max3_f32 v121, v121, v42, v58
	v_max3_f32 v121, v121, v43, v59
	v_max3_f32 v121, v121, v44, v60
	v_max3_f32 v121, v121, v45, v61
	v_max3_f32 v121, v121, v46, v62
	v_cmp_lt_i32_e32 vcc, v177, v176
	v_max3_f32 v159, v121, v47, v63
	s_nop 0
	v_cndmask_b32_e32 v121, v175, v177, vcc
	v_lshlrev_b32_e32 v121, 2, v121
	ds_bpermute_b32 v160, v121, v159
	s_waitcnt lgkmcnt(0)
	v_max_f32_e32 v160, v160, v160
	v_max_f32_e32 v159, v159, v160
	v_add_f32_e32 v160, 0x41000000, v151
	v_cmp_gt_f32_e32 vcc, v159, v160
	s_cbranch_vccz .LBB0_381
	v_max_f32_e32 v159, v159, v159
	v_max_f32_e32 v160, v151, v151
	v_max_f32_e32 v159, v160, v159
	v_sub_f32_e32 v151, v151, v159
	v_exp_f32_e32 v160, v151
	v_mov_b32_e32 v151, v159
	v_pk_mul_f32 v[30:31], v[30:31], v[160:161] op_sel_hi:[1,0]
	v_pk_mul_f32 v[28:29], v[28:29], v[160:161] op_sel_hi:[1,0]
	v_pk_mul_f32 v[26:27], v[26:27], v[160:161] op_sel_hi:[1,0]
	v_pk_mul_f32 v[24:25], v[24:25], v[160:161] op_sel_hi:[1,0]
	v_pk_mul_f32 v[22:23], v[22:23], v[160:161] op_sel_hi:[1,0]
	v_pk_mul_f32 v[20:21], v[20:21], v[160:161] op_sel_hi:[1,0]
	v_pk_mul_f32 v[18:19], v[18:19], v[160:161] op_sel_hi:[1,0]
	v_pk_mul_f32 v[16:17], v[16:17], v[160:161] op_sel_hi:[1,0]
	v_pk_mul_f32 v[14:15], v[14:15], v[160:161] op_sel_hi:[1,0]
	v_pk_mul_f32 v[12:13], v[12:13], v[160:161] op_sel_hi:[1,0]
	v_pk_mul_f32 v[10:11], v[10:11], v[160:161] op_sel_hi:[1,0]
	v_pk_mul_f32 v[8:9], v[8:9], v[160:161] op_sel_hi:[1,0]
	v_pk_mul_f32 v[6:7], v[6:7], v[160:161] op_sel_hi:[1,0]
	v_pk_mul_f32 v[4:5], v[4:5], v[160:161] op_sel_hi:[1,0]
	v_pk_mul_f32 v[2:3], v[2:3], v[160:161] op_sel_hi:[1,0]
	v_pk_mul_f32 v[0:1], v[0:1], v[160:161] op_sel_hi:[1,0]
	v_mul_f32_e32 v119, v119, v160

.Lsa_no_e0:
	s_waitcnt vmcnt(0)
	s_setprio 1
	v_add_u32_e32 v88, v154, v155
	ds_read_b128 v[32:35], v88 offset:13312
	ds_read_b128 v[48:51], v88 offset:13344
	s_waitcnt lgkmcnt(1)
	v_mfma_f32_32x32x16_bf16 v[32:47], v[32:35], v[84:87], 0
	s_waitcnt lgkmcnt(0)
	v_mfma_f32_32x32x16_bf16 v[32:47], v[48:51], v[80:83], v[32:47]
	ds_read_b128 v[48:51], v88 offset:13376
	s_waitcnt lgkmcnt(0)
	v_mfma_f32_32x32x16_bf16 v[32:47], v[48:51], v[76:79], v[32:47]
	ds_read_b128 v[48:51], v88 offset:13408
	s_waitcnt lgkmcnt(0)
	v_mfma_f32_32x32x16_bf16 v[32:47], v[48:51], v[72:75], v[32:47]
	ds_read_b128 v[48:51], v88 offset:13440
	s_waitcnt lgkmcnt(0)
	v_mfma_f32_32x32x16_bf16 v[32:47], v[48:51], v[68:71], v[32:47]
	ds_read_b128 v[48:51], v88 offset:13472
	s_waitcnt lgkmcnt(0)
	v_mfma_f32_32x32x16_bf16 v[32:47], v[48:51], v[64:67], v[32:47]
	ds_read_b128 v[48:51], v88 offset:19968
	s_waitcnt lgkmcnt(0)
	v_mfma_f32_32x32x16_bf16 v[48:63], v[48:51], v[84:87], 0
	ds_read_b128 v[84:87], v88 offset:20000
	s_waitcnt lgkmcnt(0)
	v_mfma_f32_32x32x16_bf16 v[48:63], v[84:87], v[80:83], v[48:63]
	ds_read_b128 v[80:83], v88 offset:20032
	s_waitcnt lgkmcnt(0)
	v_mfma_f32_32x32x16_bf16 v[48:63], v[80:83], v[76:79], v[48:63]
	ds_read_b128 v[76:79], v88 offset:20064
	s_waitcnt lgkmcnt(0)
	v_mfma_f32_32x32x16_bf16 v[48:63], v[76:79], v[72:75], v[48:63]
	ds_read_b128 v[72:75], v88 offset:20096
	s_waitcnt lgkmcnt(0)
	v_mfma_f32_32x32x16_bf16 v[48:63], v[72:75], v[68:71], v[48:63]
	ds_read_b128 v[68:71], v88 offset:20128
	s_waitcnt lgkmcnt(0)
	v_mfma_f32_32x32x16_bf16 v[48:63], v[68:71], v[64:67], v[48:63]
	s_setprio 0
	s_nop 10
	v_max_f32_e32 v64, v48, v48
	v_max_f32_e32 v65, v32, v32
	v_max_f32_e32 v64, v65, v64
	v_max3_f32 v64, v64, v33, v49
	v_max3_f32 v64, v64, v34, v50
	v_max3_f32 v64, v64, v35, v51
	v_max3_f32 v64, v64, v36, v52
	v_max3_f32 v64, v64, v37, v53
	v_max3_f32 v64, v64, v38, v54
	v_max3_f32 v64, v64, v39, v55
	v_max3_f32 v64, v64, v40, v56
	v_max3_f32 v64, v64, v41, v57
	v_max3_f32 v64, v64, v42, v58
	v_max3_f32 v64, v64, v43, v59
	v_max3_f32 v64, v64, v44, v60
	v_max3_f32 v64, v64, v45, v61
	v_max3_f32 v64, v64, v46, v62
	v_max3_f32 v64, v64, v47, v63
	ds_bpermute_b32 v65, v121, v64
	s_waitcnt lgkmcnt(0)
	v_max_f32_e32 v65, v65, v65
	v_max_f32_e32 v64, v64, v65
	v_add_f32_e32 v65, 0x41000000, v151
	v_cmp_gt_f32_e32 vcc, v64, v65
	s_cbranch_vccz .LBB0_351
	v_max_f32_e32 v64, v64, v64
	v_max_f32_e32 v65, v151, v151
	v_max_f32_e32 v65, v65, v64
	v_sub_f32_e32 v64, v151, v65
	v_exp_f32_e32 v64, v64
	v_mov_b32_e32 v151, v65
	v_pk_mul_f32 v[30:31], v[30:31], v[64:65] op_sel_hi:[1,0]
	v_pk_mul_f32 v[28:29], v[28:29], v[64:65] op_sel_hi:[1,0]
	v_pk_mul_f32 v[26:27], v[26:27], v[64:65] op_sel_hi:[1,0]
	v_pk_mul_f32 v[24:25], v[24:25], v[64:65] op_sel_hi:[1,0]
	v_pk_mul_f32 v[22:23], v[22:23], v[64:65] op_sel_hi:[1,0]
	v_pk_mul_f32 v[20:21], v[20:21], v[64:65] op_sel_hi:[1,0]
	v_pk_mul_f32 v[18:19], v[18:19], v[64:65] op_sel_hi:[1,0]
	v_pk_mul_f32 v[16:17], v[16:17], v[64:65] op_sel_hi:[1,0]
	v_pk_mul_f32 v[14:15], v[14:15], v[64:65] op_sel_hi:[1,0]
	v_pk_mul_f32 v[12:13], v[12:13], v[64:65] op_sel_hi:[1,0]
	v_pk_mul_f32 v[10:11], v[10:11], v[64:65] op_sel_hi:[1,0]
	v_pk_mul_f32 v[8:9], v[8:9], v[64:65] op_sel_hi:[1,0]
	v_pk_mul_f32 v[6:7], v[6:7], v[64:65] op_sel_hi:[1,0]
	v_pk_mul_f32 v[4:5], v[4:5], v[64:65] op_sel_hi:[1,0]
	v_pk_mul_f32 v[2:3], v[2:3], v[64:65] op_sel_hi:[1,0]
	v_pk_mul_f32 v[0:1], v[0:1], v[64:65] op_sel_hi:[1,0]
	v_mul_f32_e32 v119, v119, v64
	s_branch .LBB0_351
